# grid barrier: non-leader workgroups poll the top-level generation word directly instead of waiting for their XCD leader's relay
# speedup vs baseline: 1.0042x; 1.0042x over previous
; __device__ __forceinline__ unsigned xb_ld(unsigned* p)              { return __hip_atomic_load(p, __ATOMIC_RELAXED, __HIP_MEMORY_SCOPE_AGENT); }
; __device__ __forceinline__ unsigned xb_add(unsigned* p, unsigned v) { return __hip_atomic_fetch_add(p, v, __ATOMIC_RELAXED, __HIP_MEMORY_SCOPE_AGENT); }
; #define XB_SPIN(cond, bar) do { unsigned _sp = 0; while (cond) { __builtin_amdgcn_s_sleep(1); \
;     if ((++_sp & 255u) == 0u) { if (xb_ld(&(bar)[XB_TMO])) break; if (_sp > XB_SPIN_CAP) { atomicAdd(&(bar)[XB_TMO], 1u); break; } } } } while (0)
; __device__ __forceinline__ void xcd_barrier(unsigned* bar, volatile LAS unsigned* st) {
;     ...
;         const unsigned old = xb_add(&bar[XB_XSUB(x)], 1u);
;         const unsigned gen = old / nloc;
;         if (old + 1u == (gen + 1u) * nloc) {
;             __builtin_amdgcn_fence(__ATOMIC_RELEASE, "agent");
;             asm volatile("s_waitcnt vmcnt(0)" ::: "memory");
;             const unsigned og = xb_add(&bar[XB_TOP], 1u);
;             const unsigned tg = og / nx;
;             if (og + 1u == (tg + 1u) * nx) xb_add(&bar[XB_TOPGEN], 1u);
;             else XB_SPIN(xb_ld(&bar[XB_TOPGEN]) == tg, bar);
;             __builtin_amdgcn_fence(__ATOMIC_ACQUIRE, "agent");
;             xb_add(&bar[XB_XGEN(x)], 1u);
;             asm volatile("s_waitcnt vmcnt(0)" ::: "memory");
;         } else {
;             XB_SPIN(xb_ld(&bar[XB_XGEN(x)]) == gen, bar);
.LBB0_108:
	s_or_b64 exec, exec, s[6:7]
	v_cvt_f32_u32_e32 v4, v2
	s_waitcnt vmcnt(0)
	v_readfirstlane_b32 s4, v3
	v_sub_u32_e32 v3, 0, v2
	v_rcp_iflag_f32_e32 v4, v4
	v_add_u32_e32 v5, s4, v1
	v_mul_f32_e32 v4, 0x4f7ffffe, v4
	v_cvt_u32_f32_e32 v4, v4
	v_mul_lo_u32 v1, v3, v4
	v_mul_hi_u32 v1, v4, v1
	v_add_u32_e32 v1, v4, v1
	v_mul_hi_u32 v1, v5, v1
	v_mul_lo_u32 v3, v1, v2
	v_sub_u32_e32 v3, v5, v3
	v_add_u32_e32 v4, 1, v1
	v_cmp_ge_u32_e32 vcc, v3, v2
	s_nop 1
	v_cndmask_b32_e32 v1, v1, v4, vcc
	v_sub_u32_e32 v4, v3, v2
	v_cndmask_b32_e32 v3, v3, v4, vcc
	v_add_u32_e32 v4, 1, v1
	v_cmp_ge_u32_e32 vcc, v3, v2
	v_add_u32_e32 v3, 1, v5
	s_nop 0
	v_cndmask_b32_e32 v1, v1, v4, vcc
	v_mul_lo_u32 v4, v2, v1
	v_add_u32_e32 v2, v4, v2
	v_cmp_ne_u32_e32 vcc, v3, v2
	s_and_saveexec_b64 s[4:5], vcc
	s_xor_b64 s[4:5], exec, s[4:5]
	s_cbranch_execz .LBB0_122
	s_waitcnt lgkmcnt(0)
	v_mov_b32_e32 v0, 0x3500
	global_load_dword v0, v0, s[34:35] sc1
	s_add_u32 s8, s34, 0x3500
	s_addc_u32 s9, s35, 0
	s_waitcnt vmcnt(0)
	v_cmp_eq_u32_e32 vcc, v0, v1
	s_and_saveexec_b64 s[6:7], vcc
	s_cbranch_execz .LBB0_121
	s_mov_b32 s10, 1
	s_mov_b64 s[14:15], 0
	v_mov_b32_e32 v0, 0
	s_branch .LBB0_112

; __device__ __forceinline__ unsigned xb_ld(unsigned* p)              { return __hip_atomic_load(p, __ATOMIC_RELAXED, __HIP_MEMORY_SCOPE_AGENT); }
; __device__ __forceinline__ unsigned xb_add(unsigned* p, unsigned v) { return __hip_atomic_fetch_add(p, v, __ATOMIC_RELAXED, __HIP_MEMORY_SCOPE_AGENT); }
; #define XB_SPIN(cond, bar) do { unsigned _sp = 0; while (cond) { __builtin_amdgcn_s_sleep(1); \
;     if ((++_sp & 255u) == 0u) { if (xb_ld(&(bar)[XB_TMO])) break; if (_sp > XB_SPIN_CAP) { atomicAdd(&(bar)[XB_TMO], 1u); break; } } } } while (0)
; __device__ __forceinline__ void xcd_barrier(unsigned* bar, volatile LAS unsigned* st) {
;     ...
;         const unsigned old = xb_add(&bar[XB_XSUB(x)], 1u);
;         const unsigned gen = old / nloc;
;         if (old + 1u == (gen + 1u) * nloc) {
;             __builtin_amdgcn_fence(__ATOMIC_RELEASE, "agent");
;             asm volatile("s_waitcnt vmcnt(0)" ::: "memory");
;             const unsigned og = xb_add(&bar[XB_TOP], 1u);
;             const unsigned tg = og / nx;
;             if (og + 1u == (tg + 1u) * nx) xb_add(&bar[XB_TOPGEN], 1u);
;             else XB_SPIN(xb_ld(&bar[XB_TOPGEN]) == tg, bar);
;             __builtin_amdgcn_fence(__ATOMIC_ACQUIRE, "agent");
;             xb_add(&bar[XB_XGEN(x)], 1u);
;             asm volatile("s_waitcnt vmcnt(0)" ::: "memory");
;         } else {
;             XB_SPIN(xb_ld(&bar[XB_XGEN(x)]) == gen, bar);
.LBB0_1975:
	s_or_b64 exec, exec, s[6:7]
	v_cvt_f32_u32_e32 v4, v2
	s_waitcnt vmcnt(0)
	v_readfirstlane_b32 s4, v3
	v_sub_u32_e32 v3, 0, v2
	v_rcp_iflag_f32_e32 v4, v4
	v_add_u32_e32 v5, s4, v1
	v_mul_f32_e32 v4, 0x4f7ffffe, v4
	v_cvt_u32_f32_e32 v4, v4
	v_mul_lo_u32 v1, v3, v4
	v_mul_hi_u32 v1, v4, v1
	v_add_u32_e32 v1, v4, v1
	v_mul_hi_u32 v1, v5, v1
	v_mul_lo_u32 v3, v1, v2
	v_sub_u32_e32 v3, v5, v3
	v_add_u32_e32 v4, 1, v1
	v_cmp_ge_u32_e32 vcc, v3, v2
	s_nop 1
	v_cndmask_b32_e32 v1, v1, v4, vcc
	v_sub_u32_e32 v4, v3, v2
	v_cndmask_b32_e32 v3, v3, v4, vcc
	v_add_u32_e32 v4, 1, v1
	v_cmp_ge_u32_e32 vcc, v3, v2
	v_add_u32_e32 v3, 1, v5
	s_nop 0
	v_cndmask_b32_e32 v1, v1, v4, vcc
	v_mul_lo_u32 v4, v2, v1
	v_add_u32_e32 v2, v4, v2
	v_cmp_ne_u32_e32 vcc, v3, v2
	s_and_saveexec_b64 s[4:5], vcc
	s_xor_b64 s[4:5], exec, s[4:5]
	s_cbranch_execz .LBB0_1989
	s_waitcnt lgkmcnt(0)
	v_mov_b32_e32 v0, 0x3500
	global_load_dword v0, v0, s[34:35] sc1
	s_add_u32 s8, s34, 0x3500
	s_addc_u32 s9, s35, 0
	s_waitcnt vmcnt(0)
	v_cmp_eq_u32_e32 vcc, v0, v1
	s_and_saveexec_b64 s[6:7], vcc
	s_cbranch_execz .LBB0_1988
	s_mov_b32 s20, 1
	s_mov_b64 s[10:11], 0
	v_mov_b32_e32 v0, 0
	s_branch .LBB0_1979
